# as v19 with the leader's now-unused per-XCD relay atomic removed from the grid barrier
# baseline (speedup 1.0000x reference)
; __device__ __forceinline__ unsigned xb_ld(unsigned* p)              { return __hip_atomic_load(p, __ATOMIC_RELAXED, __HIP_MEMORY_SCOPE_AGENT); }
; __device__ __forceinline__ unsigned xb_add(unsigned* p, unsigned v) { return __hip_atomic_fetch_add(p, v, __ATOMIC_RELAXED, __HIP_MEMORY_SCOPE_AGENT); }
; #define XB_SPIN(cond, bar) do { unsigned _sp = 0; while (cond) { __builtin_amdgcn_s_sleep(1); \
;     if ((++_sp & 255u) == 0u) { if (xb_ld(&(bar)[XB_TMO])) break; if (_sp > XB_SPIN_CAP) { atomicAdd(&(bar)[XB_TMO], 1u); break; } } } } while (0)
; __device__ __forceinline__ void xcd_barrier(const XcdBarrier& b) {
;     ...
;             else XB_SPIN(xb_ld(&bar[XB_TOPGEN]) == tg, bar);
;             __builtin_amdgcn_fence(__ATOMIC_ACQUIRE, "agent");
;             xb_add(&bar[XB_XGEN(b.x)], 1u);
;             asm volatile("s_waitcnt vmcnt(0)" ::: "memory");
.LBB0_139:
	s_or_b64 exec, exec, s[4:5]
	s_mov_b64 s[4:5], exec
	v_mbcnt_lo_u32_b32 v4, s4, 0
	v_mbcnt_hi_u32_b32 v4, s5, v4
	v_cmp_eq_u32_e32 vcc, 0, v4
	s_waitcnt vmcnt(0)
	buffer_inv sc1
	s_and_saveexec_b64 s[24:25], vcc
	s_cbranch_execz .LBB0_141
	s_bcnt1_i32_b64 s4, s[4:5]
	v_mov_b32_e32 v4, s4
	v_readlane_b32 s4, v249, 45
	v_readlane_b32 s5, v249, 46
	s_nop 4
	s_nop 0

; __device__ __forceinline__ unsigned xb_ld(unsigned* p)              { return __hip_atomic_load(p, __ATOMIC_RELAXED, __HIP_MEMORY_SCOPE_AGENT); }
; __device__ __forceinline__ unsigned xb_add(unsigned* p, unsigned v) { return __hip_atomic_fetch_add(p, v, __ATOMIC_RELAXED, __HIP_MEMORY_SCOPE_AGENT); }
; #define XB_SPIN(cond, bar) do { unsigned _sp = 0; while (cond) { __builtin_amdgcn_s_sleep(1); \
;     if ((++_sp & 255u) == 0u) { if (xb_ld(&(bar)[XB_TMO])) break; if (_sp > XB_SPIN_CAP) { atomicAdd(&(bar)[XB_TMO], 1u); break; } } } } while (0)
; __device__ __forceinline__ void xcd_barrier(const XcdBarrier& b) {
;     ...
;             else XB_SPIN(xb_ld(&bar[XB_TOPGEN]) == tg, bar);
;             __builtin_amdgcn_fence(__ATOMIC_ACQUIRE, "agent");
;             xb_add(&bar[XB_XGEN(b.x)], 1u);
;             asm volatile("s_waitcnt vmcnt(0)" ::: "memory");
.LBB0_207:
	s_or_b64 exec, exec, s[24:25]
	s_mov_b64 s[24:25], exec
	v_mbcnt_lo_u32_b32 v4, s24, 0
	v_mbcnt_hi_u32_b32 v4, s25, v4
	v_cmp_eq_u32_e32 vcc, 0, v4
	s_waitcnt vmcnt(0)
	buffer_inv sc1
	s_and_saveexec_b64 s[26:27], vcc
	s_cbranch_execz .LBB0_209
	s_bcnt1_i32_b64 s24, s[24:25]
	v_mov_b32_e32 v4, s24
	v_readlane_b32 s24, v249, 45
	v_readlane_b32 s25, v249, 46
	s_nop 4
	s_nop 0

; __device__ __forceinline__ unsigned xb_ld(unsigned* p)              { return __hip_atomic_load(p, __ATOMIC_RELAXED, __HIP_MEMORY_SCOPE_AGENT); }
; __device__ __forceinline__ unsigned xb_add(unsigned* p, unsigned v) { return __hip_atomic_fetch_add(p, v, __ATOMIC_RELAXED, __HIP_MEMORY_SCOPE_AGENT); }
; #define XB_SPIN(cond, bar) do { unsigned _sp = 0; while (cond) { __builtin_amdgcn_s_sleep(1); \
;     if ((++_sp & 255u) == 0u) { if (xb_ld(&(bar)[XB_TMO])) break; if (_sp > XB_SPIN_CAP) { atomicAdd(&(bar)[XB_TMO], 1u); break; } } } } while (0)
; __device__ __forceinline__ void xcd_barrier(const XcdBarrier& b) {
;     ...
;             else XB_SPIN(xb_ld(&bar[XB_TOPGEN]) == tg, bar);
;             __builtin_amdgcn_fence(__ATOMIC_ACQUIRE, "agent");
;             xb_add(&bar[XB_XGEN(b.x)], 1u);
;             asm volatile("s_waitcnt vmcnt(0)" ::: "memory");
.LBB0_408:
	s_or_b64 exec, exec, s[24:25]
	s_mov_b64 s[24:25], exec
	v_mbcnt_lo_u32_b32 v4, s24, 0
	v_mbcnt_hi_u32_b32 v4, s25, v4
	v_cmp_eq_u32_e32 vcc, 0, v4
	s_waitcnt vmcnt(0)
	buffer_inv sc1
	s_and_saveexec_b64 s[26:27], vcc
	s_cbranch_execz .LBB0_410
	s_bcnt1_i32_b64 s20, s[24:25]
	v_readlane_b32 s24, v249, 45
	v_mov_b32_e32 v4, s20
	v_readlane_b32 s25, v249, 46
	s_nop 4
	s_nop 0

; __device__ __forceinline__ unsigned xb_ld(unsigned* p)              { return __hip_atomic_load(p, __ATOMIC_RELAXED, __HIP_MEMORY_SCOPE_AGENT); }
; __device__ __forceinline__ unsigned xb_add(unsigned* p, unsigned v) { return __hip_atomic_fetch_add(p, v, __ATOMIC_RELAXED, __HIP_MEMORY_SCOPE_AGENT); }
; #define XB_SPIN(cond, bar) do { unsigned _sp = 0; while (cond) { __builtin_amdgcn_s_sleep(1); \
;     if ((++_sp & 255u) == 0u) { if (xb_ld(&(bar)[XB_TMO])) break; if (_sp > XB_SPIN_CAP) { atomicAdd(&(bar)[XB_TMO], 1u); break; } } } } while (0)
; __device__ __forceinline__ void xcd_barrier(const XcdBarrier& b) {
;     ...
;             else XB_SPIN(xb_ld(&bar[XB_TOPGEN]) == tg, bar);
;             __builtin_amdgcn_fence(__ATOMIC_ACQUIRE, "agent");
;             xb_add(&bar[XB_XGEN(b.x)], 1u);
;             asm volatile("s_waitcnt vmcnt(0)" ::: "memory");
.LBB0_687:
	s_or_b64 exec, exec, s[4:5]
	s_mov_b64 s[4:5], exec
	v_mbcnt_lo_u32_b32 v4, s4, 0
	v_mbcnt_hi_u32_b32 v4, s5, v4
	v_cmp_eq_u32_e32 vcc, 0, v4
	s_waitcnt vmcnt(0)
	buffer_inv sc1
	s_and_saveexec_b64 s[24:25], vcc
	s_cbranch_execz .LBB0_71
	s_bcnt1_i32_b64 s4, s[4:5]
	v_mov_b32_e32 v4, s4
	v_readlane_b32 s4, v249, 45
	v_readlane_b32 s5, v249, 46
	s_nop 4
	s_nop 0
	s_branch .LBB0_71
